# H + attention next-unit Q/mask prefetch during last key pair, K/V DMA wait moved to pair end so O stores are not drained
# baseline (speedup 1.0000x reference)
; #define LAS __attribute__((address_space(3)))
; __device__ __forceinline__ void attn_unit(const Params& p, LAS unsigned char* lds, int b, int h, int qb, int tid, int wid, int lane, u64& tacc, v4u& kA, v4u& vA, v4u& kB, v4u& vB, const bool first) {
;     ...
;     const size_t rowbase = (size_t)b * SEQ; const int q0 = qb * 256;
;     LAS bf16* stg = (LAS bf16*)(lds + 32768) + wid * 2304;
;     const bf16* Qw = proj + (rowbase + q0 + wid * 32) * NPROJ + PC_Q + h * 64;
;     bf16x8 qr[4];
; #pragma unroll
;     for (int d0 = 0; d0 < 4; ++d0) qr[d0] = *(const bf16x8*)(Qw + (size_t)r32 * NPROJ + d0 * 16 + hi * 8);
;     const int NT = 4 * (qb + 1); const int tcw = 4 * qb + (wid >> 1);
;     const bf16* ksrc = (const bf16*)((const unsigned char*)p.out + DO_KBLK) + (size_t)(b * 8 + h) * 64 * 4096 + wid * 512 + lane * 8;
;     const bf16* vsrc = (const bf16*)((const unsigned char*)p.out + DO_VBLK) + (size_t)(b * 8 + h) * 64 * 4096 + wid * 512 + lane * 8;
;     const u64* bmq = bm + (rowbase + q0 + wid * 32 + r32) * 64;
.LBB0_3754:
	s_ashr_i32 s0, s85, 5
	s_ashr_i32 s1, s0, 31
	s_and_b32 s38, s85, 3
	s_bfe_u32 s2, s85, 0x30002
	s_lshl_b64 s[4:5], s[0:1], 12
	s_add_u32 s39, s4, s24
	s_addc_u32 s40, s5, 0
	s_lshl_b32 s0, s0, 3
	s_or_b32 s0, s0, s2
	s_ashr_i32 s1, s0, 31
	s_lshl_b64 s[0:1], s[0:1], 19
	s_lshl_b32 s9, s2, 6
	v_lshl_add_u64 v[180:181], v[162:163], 0, s[0:1]
	v_lshl_add_u64 v[182:183], v[164:165], 0, s[0:1]
	s_lshl_b32 s2, s2, 7
	s_or_b32 s41, s38, 8
	s_xor_b32 s42, s38, 15
	s_xor_b32 s43, s38, 7
	v_lshl_add_u64 v[184:185], v[180:181], 0, s[12:13]
	v_lshl_add_u64 v[186:187], v[182:183], 0, s[12:13]
	v_lshl_add_u64 v[192:193], v[166:167], 0, s[2:3]
	v_lshl_add_u64 v[194:195], v[168:169], 0, s[4:5]
	s_lshl_b32 s44, s9, 1
	s_mov_b32 s45, s3
	s_branch .LBB0_3756
.Lq_last:
	s_cmp_eq_u32 s45, 3
	s_cbranch_scc1 .LBB0_3761
	s_add_i32 s52, s45, 1
	s_cmp_eq_u32 s52, 2
	s_cselect_b32 s53, s41, s42
	s_cmp_eq_u32 s52, 1
	s_cselect_b32 s53, s43, s53
	s_lshl_b32 s53, s53, 8
	s_add_u32 s54, s39, s53
	s_addc_u32 s55, s40, 0
	s_mul_i32 s1, s55, 0x2a00
	s_mul_hi_u32 s0, s54, 0x2a00
	s_add_i32 s0, s0, s1
	s_mul_i32 s1, s54, 0x2a00
	s_add_u32 s1, s82, s1
	s_addc_u32 s57, s83, s0
	s_add_u32 s56, s1, s44
	s_addc_u32 s57, s57, 0
	v_mov_b32_e32 v10, v170
	v_mov_b32_e32 v11, v159
	v_lshl_add_u64 v[6:7], s[56:57], 0, v[158:159]
	v_lshl_add_u64 v[6:7], v[6:7], 0, v[10:11]
	v_lshl_add_u64 v[8:9], v[6:7], 0, s[16:17]
	v_add_co_u32_e32 v6, vcc, s26, v6
	s_nop 1
	v_addc_co_u32_e32 v7, vcc, 0, v7, vcc
	v_mov_b32_e32 v11, s55
	v_or_b32_e32 v10, s54, v156
	v_lshlrev_b64 v[10:11], 9, v[10:11]
	v_lshl_add_u64 v[10:11], s[80:81], 0, v[10:11]
	global_load_dwordx4 v[120:123], v[8:9], off offset:32
	global_load_dwordx4 v[124:127], v[8:9], off offset:64
	global_load_dwordx4 v[128:131], v[6:7], off offset:2048
	global_load_dwordx4 v[132:135], v[8:9], off offset:96
	global_load_dwordx4 v[188:191], v[10:11], off
	s_branch .LBB0_3761

; #define LAS __attribute__((address_space(3)))
; __device__ __forceinline__ void attn_unit(const Params& p, LAS unsigned char* lds, int b, int h, int qb, int tid, int wid, int lane, u64& tacc, v4u& kA, v4u& vA, v4u& kB, v4u& vB, const bool first) {
;     ...
;     const bf16* Qw = proj + (rowbase + q0 + wid * 32) * NPROJ + PC_Q + h * 64;
;     bf16x8 qr[4];
; #pragma unroll
;     for (int d0 = 0; d0 < 4; ++d0) qr[d0] = *(const bf16x8*)(Qw + (size_t)r32 * NPROJ + d0 * 16 + hi * 8);
;     const int NT = 4 * (qb + 1); const int tcw = 4 * qb + (wid >> 1);
;     const bf16* ksrc = (const bf16*)((const unsigned char*)p.out + DO_KBLK) + (size_t)(b * 8 + h) * 64 * 4096 + wid * 512 + lane * 8;
;     const bf16* vsrc = (const bf16*)((const unsigned char*)p.out + DO_VBLK) + (size_t)(b * 8 + h) * 64 * 4096 + wid * 512 + lane * 8;
;     const u64* bmq = bm + (rowbase + q0 + wid * 32 + r32) * 64;
;     const unsigned stoff = wid * 1024 + lane * 16;
;     const unsigned vboff = 8192 + ((lane >> 4) & 1) * 32 + (lane & 3) * 8 + (4 * hi + ((lane & 15) >> 2)) * 64;
;     float m = 0.f; bool started = false; f32x16 o0, o1, o2;
; #pragma unroll
;     for (int i = 0; i < 16; ++i) { o0[i] = 0.f; o1[i] = 0.f; o2[i] = 0.f; }
;     float negv = -1e30f; asm volatile("" : "+v"(negv));
;     const bf16x8 ones8 = (bf16x8){0x3f80, 0x3f80, 0x3f80, 0x3f80, 0x3f80, 0x3f80, 0x3f80, 0x3f80};
;     v4u mwc = *(const v4u*)bmq, mwn = mwc;
;     if (first) {
;         kB = *(const v4u*)ksrc; vB = *(const v4u*)vsrc;
;         kA = *(const v4u*)(ksrc + (size_t)4096); vA = *(const v4u*)(vsrc + (size_t)4096);
;         *(LAS v4u*)(lds + stoff) = kB; *(LAS v4u*)(lds + 8192 + stoff) = vB;
;         kB = *(const v4u*)(ksrc + (size_t)2 * 4096); vB = *(const v4u*)(vsrc + (size_t)2 * 4096);
;     }
;     bf16x8 Eop[2];
; #pragma unroll
;     for (int s = 0; s < 2; ++s) { v4u e; unsigned* ep = (unsigned*)&e;
; #pragma unroll
;         for (int i = 0; i < 4; ++i) { const int k0 = 4 * s + i + 8 * hi; ep[i] = (r32 == k0 ? 0x3F80u : 0u) | (r32 == k0 + 16 ? 0x3F800000u : 0u); }
;         Eop[s] = __builtin_bit_cast(bf16x8, e); }
;     f32x16 nsplat;
; #pragma unroll
;     for (int r = 0; r < 16; ++r) nsplat[r] = -m;
.LBB0_3756:
	s_cmp_eq_u32 s45, 2
	s_cselect_b32 s0, s41, s42
	s_cmp_eq_u32 s45, 1
	s_cselect_b32 s0, s43, s0
	s_cmp_eq_u32 s45, 0
	s_cselect_b32 s0, s38, s0
	s_lshl_b32 s2, s0, 8
	s_add_u32 s18, s39, s2
	s_addc_u32 s19, s40, 0
	s_mul_i32 s1, s19, 0x2a00
	s_mul_hi_u32 s4, s18, 0x2a00
	s_add_i32 s4, s4, s1
	s_mul_i32 s1, s18, 0x2a00
	s_add_u32 s1, s82, s1
	s_addc_u32 s5, s83, s4
	s_add_u32 s4, s1, s44
	s_addc_u32 s5, s5, 0
	s_cmp_lg_u32 s45, 0
	s_cbranch_scc1 .Lq_copy
	v_lshl_add_u64 v[2:3], s[4:5], 0, v[158:159]
	v_mov_b32_e32 v171, v159
	v_lshl_add_u64 v[2:3], v[2:3], 0, v[170:171]
	v_lshl_add_u64 v[4:5], v[2:3], 0, s[16:17]
	v_add_co_u32_e32 v2, vcc, s26, v2
	v_mov_b32_e32 v1, 0xf149f2ca
	s_nop 0
	v_addc_co_u32_e32 v3, vcc, 0, v3, vcc
	global_load_dwordx4 v[136:139], v[4:5], off offset:32
	global_load_dwordx4 v[140:143], v[4:5], off offset:64
	global_load_dwordx4 v[144:147], v[2:3], off offset:2048
	global_load_dwordx4 v[148:151], v[4:5], off offset:96
	v_mov_b32_e32 v3, s19
	v_or_b32_e32 v2, s18, v156
	v_lshlrev_b64 v[2:3], 9, v[2:3]
	v_lshl_add_u64 v[2:3], s[80:81], 0, v[2:3]
	global_load_dwordx4 v[152:155], v[2:3], off
	s_mov_b32 m0, s75
	s_nop 0
	global_load_lds_dwordx4 v[180:181], off
	s_add_i32 m0, s75, 0x2000
	s_nop 0
	global_load_lds_dwordx4 v[182:183], off
	s_add_i32 m0, s75, 0x4000
	s_nop 0
	global_load_lds_dwordx4 v[184:185], off
	s_add_i32 m0, s75, 0x6000
	s_nop 0
	global_load_lds_dwordx4 v[186:187], off
	s_waitcnt vmcnt(0)
	s_branch .LBB0_3758
.Lq_copy:
	s_waitcnt vmcnt(4)
	v_mov_b64_e32 v[136:137], v[120:121]
	v_mov_b64_e32 v[138:139], v[122:123]
	v_mov_b64_e32 v[140:141], v[124:125]
	v_mov_b64_e32 v[142:143], v[126:127]
	v_mov_b64_e32 v[144:145], v[128:129]
	v_mov_b64_e32 v[146:147], v[130:131]
	v_mov_b64_e32 v[148:149], v[132:133]
	v_mov_b64_e32 v[150:151], v[134:135]
	v_mov_b64_e32 v[152:153], v[188:189]
	v_mov_b64_e32 v[154:155], v[190:191]
.LBB0_3758:
	v_lshl_add_u64 v[2:3], v[194:195], 0, s[2:3]
	v_lshlrev_b64 v[2:3], 9, v[2:3]
	v_mov_b32_e32 v14, v0
	v_mov_b32_e32 v15, v0
	v_lshl_add_u64 v[196:197], s[6:7], 0, v[2:3]
	v_mov_b32_e32 v1, v0
	v_mov_b32_e32 v2, v0
	v_mov_b32_e32 v3, v0
	v_mov_b32_e32 v4, v0
	v_mov_b32_e32 v5, v0
	v_mov_b32_e32 v6, v0
	v_mov_b32_e32 v7, v0
	v_mov_b32_e32 v8, v0
	v_mov_b32_e32 v9, v0
	v_mov_b32_e32 v10, v0
	v_mov_b32_e32 v11, v0
	v_mov_b32_e32 v12, v0
	v_mov_b32_e32 v13, v0
	v_mov_b32_e32 v30, v159
	v_mov_b32_e32 v31, v159
	v_mov_b64_e32 v[78:79], v[14:15]
	s_lshl_b32 s46, s0, 2
	v_mov_b32_e32 v16, v159
	v_mov_b32_e32 v17, v159
	v_mov_b32_e32 v18, v159
	v_mov_b32_e32 v19, v159
	v_mov_b32_e32 v20, v159
	v_mov_b32_e32 v21, v159
	v_mov_b32_e32 v22, v159
	v_mov_b32_e32 v23, v159
	v_mov_b32_e32 v24, v159
	v_mov_b32_e32 v25, v159
	v_mov_b32_e32 v26, v159
	v_mov_b32_e32 v27, v159
	v_mov_b32_e32 v28, v159
	v_mov_b32_e32 v29, v159
	v_mov_b64_e32 v[46:47], v[30:31]
	v_mov_b64_e32 v[62:63], v[30:31]
	v_mov_b64_e32 v[76:77], v[12:13]
	v_mov_b64_e32 v[74:75], v[10:11]
	v_mov_b64_e32 v[72:73], v[8:9]
	v_mov_b64_e32 v[70:71], v[6:7]
	v_mov_b64_e32 v[68:69], v[4:5]
	v_mov_b64_e32 v[66:67], v[2:3]
	v_mov_b64_e32 v[64:65], v[0:1]
	v_mov_b64_e32 v[2:3], v[152:153]
	s_add_i32 s47, s46, s25
	s_add_i32 s48, s46, 4
	s_mov_b32 s51, 0
	s_sub_i32 s49, 0, s46
	s_mov_b64 s[20:21], 0
	v_mov_b32_e32 v171, 0
	v_mov_b64_e32 v[44:45], v[28:29]
	v_mov_b64_e32 v[42:43], v[26:27]
	v_mov_b64_e32 v[40:41], v[24:25]
	v_mov_b64_e32 v[38:39], v[22:23]
	v_mov_b64_e32 v[36:37], v[20:21]
	v_mov_b64_e32 v[34:35], v[18:19]
	v_mov_b64_e32 v[32:33], v[16:17]
	v_mov_b64_e32 v[60:61], v[28:29]
	v_mov_b64_e32 v[58:59], v[26:27]
	v_mov_b64_e32 v[56:57], v[24:25]
	v_mov_b64_e32 v[54:55], v[22:23]
	v_mov_b64_e32 v[52:53], v[20:21]
	v_mov_b64_e32 v[50:51], v[18:19]
	v_mov_b64_e32 v[48:49], v[16:17]
	v_mov_b64_e32 v[4:5], v[154:155]
.LBB0_3759:
	s_add_i32 s50, s51, 2
	s_cmp_ge_u32 s50, s48
	s_cselect_b64 s[22:23], -1, 0
	v_xor_b32_e32 v200, 0x8000, v200
	v_xor_b32_e32 v157, 0x8000, v157
	s_xor_b32 s74, s74, 0x8000
	s_add_i32 s70, s74, s75
	s_waitcnt lgkmcnt(0)
	s_barrier
	s_and_b64 vcc, exec, s[22:23]
	s_cbranch_vccnz .Lq_last
	global_load_dwordx4 v[2:5], v[196:197], off

; __device__ __forceinline__ void attn_unit(const Params& p, LAS unsigned char* lds, int b, int h, int qb, int tid, int wid, int lane, u64& tacc, v4u& kA, v4u& vA, v4u& kB, v4u& vB, const bool first) {
;     ...
;     for (int tt = 0; tt < NT; tt += 2) {
;         if (tt + 2 < NT) mwn = *(const v4u*)(bmq + tt + 2);
;         ATT_STEP(tt, kA, vA, mwc.x, mwc.y, 0);
;         ATT_STEP(tt + 1, kB, vB, mwc.z, mwc.w, 1);
;         mwc = mwn;
;     }
.LBB0_3770:
	s_andn2_b64 vcc, exec, s[22:23]
	v_lshl_add_u64 v[196:197], v[196:197], 0, 16
	s_cbranch_vccz .LBB0_3755
	s_waitcnt vmcnt(0)
	v_mov_b64_e32 v[154:155], v[4:5]
	v_mov_b64_e32 v[152:153], v[2:3]
	s_mov_b32 s51, s50
	s_branch .LBB0_3759
